# gate-up epilogue start: one global_load_dword per wave touches the NEXT tile's 4 KiB of row statistics so the LDS-DMA fetch in its first K iteration hits L2
# baseline (speedup 1.0000x reference)
;     __device__ __forceinline__ void operator()(const f32x4 (&acc)[2][2][4][2], const Unit& u, int wr, int wc, int fr, int fq) const {
;         const int row0 = u.pm * BM + wr * 64 + fr, col0 = u.pn * HALF + wc * 32 + 8 * fq;
;         float rsv[2][4]; rstd8(ss, row0, rsv);
.Lep_fast:
	s_and_b64 vcc, s[8:9], exec
	s_cselect_b32 s4, s36, s54
	s_lshl_b32 s4, s4, 12
	v_mbcnt_lo_u32_b32 v193, -1, 0
	v_mbcnt_hi_u32_b32 v193, -1, v193
	v_lshl_add_u32 v193, v193, 6, s4
	global_load_dword v193, v193, s[24:25]
	s_lshl_b32 s4, s54, 8
	s_add_i32 s4, s4, s89
	v_or_b32_e32 v178, s4, v183
	s_lshl_b32 s5, s0, 1
	v_lshl_or_b32 v179, s48, 7, v184
	s_lshl_b32 s30, s5, 4
	s_mul_i32 s31, s5, 80
	v_mul_lo_u32 v190, v178, s5
	s_cmp_eq_u32 s54, s98
	v_lshl_add_u32 v190, v179, 1, v190
	s_cbranch_scc1 .Lep_have_rs
	s_lshl_b32 s4, s89, 4
	s_add_i32 s4, s4, 0x23000
	v_lshl_add_u32 v178, v183, 4, s4
	ds_read_b128 v[146:149], v178
	ds_read_b128 v[150:153], v178 offset:256
	ds_read_b128 v[154:157], v178 offset:512
	ds_read_b128 v[158:161], v178 offset:768
	ds_read_b128 v[162:165], v178 offset:2048
	ds_read_b128 v[166:169], v178 offset:2304
	ds_read_b128 v[170:173], v178 offset:2560
	ds_read_b128 v[174:177], v178 offset:2816
	s_mov_b32 s98, s54
	s_waitcnt lgkmcnt(0)
	v_add_f32_e32 v146, v146, v147
	v_add_f32_e32 v148, v148, v149
	v_add_f32_e32 v150, v150, v151
	v_add_f32_e32 v152, v152, v153
	v_add_f32_e32 v154, v154, v155
	v_add_f32_e32 v156, v156, v157
	v_add_f32_e32 v158, v158, v159
	v_add_f32_e32 v160, v160, v161
	v_add_f32_e32 v162, v162, v163
	v_add_f32_e32 v164, v164, v165
	v_add_f32_e32 v166, v166, v167
	v_add_f32_e32 v168, v168, v169
	v_add_f32_e32 v170, v170, v171
	v_add_f32_e32 v172, v172, v173
	v_add_f32_e32 v174, v174, v175
	v_add_f32_e32 v176, v176, v177
	v_add_f32_e32 v146, v146, v148
	v_add_f32_e32 v150, v150, v152
	v_add_f32_e32 v154, v154, v156
	v_add_f32_e32 v158, v158, v160
	v_add_f32_e32 v162, v162, v164
	v_add_f32_e32 v166, v166, v168
	v_add_f32_e32 v170, v170, v172
	v_add_f32_e32 v174, v174, v176
	v_fmamk_f32 v241, v146, 0x3a800000, v224
	v_fmamk_f32 v243, v150, 0x3a800000, v224
	v_fmamk_f32 v245, v154, 0x3a800000, v224
	v_fmamk_f32 v247, v158, 0x3a800000, v224
	v_fmamk_f32 v249, v162, 0x3a800000, v224
	v_fmamk_f32 v251, v166, 0x3a800000, v224
	v_fmamk_f32 v253, v170, 0x3a800000, v224
	v_fmamk_f32 v215, v174, 0x3a800000, v224
	v_rsq_f32_e32 v240, v241
	v_rsq_f32_e32 v242, v243
	v_rsq_f32_e32 v244, v245
	v_rsq_f32_e32 v246, v247
	v_rsq_f32_e32 v248, v249
	v_rsq_f32_e32 v250, v251
	v_rsq_f32_e32 v252, v253
	v_rsq_f32_e32 v214, v215
	s_nop 0
	v_mul_f32_e32 v240, 0xbfb8aa3b, v240
	v_mul_f32_e32 v242, 0xbfb8aa3b, v242
	v_mul_f32_e32 v244, 0xbfb8aa3b, v244
	v_mul_f32_e32 v246, 0xbfb8aa3b, v246
	v_mul_f32_e32 v248, 0xbfb8aa3b, v248
	v_mul_f32_e32 v250, 0xbfb8aa3b, v250
	v_mul_f32_e32 v252, 0xbfb8aa3b, v252
	v_mul_f32_e32 v214, 0xbfb8aa3b, v214
